# dil_attn softmax: two interleaved max chains, fma-form exp argument, O zeroing only on first group
# baseline (speedup 1.0000x reference)
.LBB0_274:
	v_max_f32_e32 v15, v97, v96
	v_max_f32_e32 v239, v39, v38
	v_max3_f32 v15, v15, v65, v64
	v_max3_f32 v239, v239, v41, v40
	v_max3_f32 v15, v15, v67, v66
	v_max3_f32 v239, v239, v43, v42
	v_max3_f32 v15, v15, v69, v68
	v_max3_f32 v239, v239, v45, v44
	v_max3_f32 v15, v15, v71, v70
	v_max3_f32 v239, v239, v47, v46
	v_max3_f32 v15, v15, v73, v72
	v_max3_f32 v239, v239, v17, v16
	v_max3_f32 v15, v15, v75, v74
	v_max3_f32 v239, v239, v19, v18
	v_max3_f32 v15, v15, v77, v76
	v_max3_f32 v239, v239, v21, v20
	v_max3_f32 v15, v15, v79, v78
	v_max3_f32 v239, v239, v23, v22
	v_max3_f32 v15, v15, v49, v48
	v_max3_f32 v239, v239, v25, v24
	v_max3_f32 v15, v15, v51, v50
	v_max3_f32 v239, v239, v27, v26
	v_max3_f32 v15, v15, v53, v52
	v_max3_f32 v239, v239, v29, v28
	v_max3_f32 v15, v15, v55, v54
	v_max3_f32 v239, v239, v31, v30
	v_max3_f32 v15, v15, v57, v56
	v_max3_f32 v239, v239, v235, v1
	v_max3_f32 v15, v15, v59, v58
	v_max3_f32 v239, v239, v3, v2
	v_max3_f32 v15, v15, v61, v60
	v_max3_f32 v239, v239, v5, v4
	v_max3_f32 v15, v15, v63, v62
	v_max3_f32 v239, v239, v7, v6
	v_max3_f32 v15, v15, v98, v32
	v_max3_f32 v239, v239, v9, v8
	v_max3_f32 v15, v15, v176, v99
	v_max3_f32 v239, v239, v11, v10
	v_max3_f32 v15, v15, v37, v36
	v_max3_f32 v239, v239, v13, v12
	s_waitcnt lgkmcnt(1)
	v_max3_f32 v15, v15, v239, v14
	ds_bpermute_b32 v35, v114, v15
	s_and_b64 vcc, exec, s[34:35]
	s_waitcnt lgkmcnt(0)
	v_max_f32_e32 v35, v35, v35
	v_max_f32_e32 v35, v15, v35
	v_mul_f32_e32 v255, 0xbfb8aa3b, v35
	v_fmamk_f32 v15, v97, 0x3fb8aa3b, v255
	v_exp_f32_e32 v198, v15
	v_fmamk_f32 v15, v65, 0x3fb8aa3b, v255
	v_exp_f32_e32 v201, v15
	v_fmamk_f32 v15, v64, 0x3fb8aa3b, v255
	v_fmamk_f32 v64, v67, 0x3fb8aa3b, v255
	v_exp_f32_e32 v217, v64
	v_fmamk_f32 v64, v66, 0x3fb8aa3b, v255
	v_exp_f32_e32 v221, v64
	v_fmamk_f32 v64, v69, 0x3fb8aa3b, v255
	v_exp_f32_e32 v222, v64
	v_fmamk_f32 v64, v68, 0x3fb8aa3b, v255
	v_exp_f32_e32 v225, v64
	v_fmamk_f32 v64, v71, 0x3fb8aa3b, v255
	v_fmamk_f32 v96, v96, 0x3fb8aa3b, v255
	v_exp_f32_e32 v215, v64
	v_fmamk_f32 v64, v70, 0x3fb8aa3b, v255
	v_exp_f32_e32 v199, v96
	v_exp_f32_e32 v218, v64
	v_fmamk_f32 v64, v73, 0x3fb8aa3b, v255
	v_fmamk_f32 v48, v48, 0x3fb8aa3b, v255
	v_exp_f32_e32 v214, v15
	v_exp_f32_e32 v219, v64
	v_fmamk_f32 v64, v72, 0x3fb8aa3b, v255
	v_add_f32_e32 v15, 0, v198
	v_exp_f32_e32 v197, v48
	v_fmamk_f32 v48, v51, 0x3fb8aa3b, v255
	v_add_f32_e32 v15, v199, v15
	v_exp_f32_e32 v223, v64
	v_fmamk_f32 v64, v75, 0x3fb8aa3b, v255
	v_add_f32_e32 v15, v201, v15
	v_exp_f32_e32 v200, v48
	v_fmamk_f32 v48, v50, 0x3fb8aa3b, v255
	v_add_f32_e32 v15, v214, v15
	v_exp_f32_e32 v226, v64
	v_fmamk_f32 v64, v74, 0x3fb8aa3b, v255
	v_add_f32_e32 v15, v217, v15
	v_exp_f32_e32 v213, v48
	v_fmamk_f32 v48, v53, 0x3fb8aa3b, v255
	v_add_f32_e32 v15, v221, v15
	v_exp_f32_e32 v229, v64
	v_fmamk_f32 v64, v77, 0x3fb8aa3b, v255
	v_add_f32_e32 v15, v222, v15
	v_exp_f32_e32 v216, v48
	v_fmamk_f32 v48, v52, 0x3fb8aa3b, v255
	v_add_f32_e32 v15, v225, v15
	v_exp_f32_e32 v230, v64
	v_fmamk_f32 v64, v76, 0x3fb8aa3b, v255
	v_add_f32_e32 v15, v215, v15
	v_exp_f32_e32 v220, v48
	v_fmamk_f32 v48, v55, 0x3fb8aa3b, v255
	v_add_f32_e32 v15, v218, v15
	v_exp_f32_e32 v232, v64
	v_fmamk_f32 v64, v79, 0x3fb8aa3b, v255
	v_add_f32_e32 v15, v219, v15
	v_exp_f32_e32 v224, v48
	v_fmamk_f32 v48, v54, 0x3fb8aa3b, v255
	v_add_f32_e32 v15, v223, v15
	v_exp_f32_e32 v194, v64
	v_fmamk_f32 v64, v78, 0x3fb8aa3b, v255
	v_add_f32_e32 v15, v226, v15
	v_fmamk_f32 v49, v49, 0x3fb8aa3b, v255
	v_exp_f32_e32 v227, v48
	v_fmamk_f32 v48, v57, 0x3fb8aa3b, v255
	v_add_f32_e32 v15, v229, v15
	v_exp_f32_e32 v195, v64
	v_add_f32_e32 v15, v230, v15
	v_exp_f32_e32 v196, v49
	v_exp_f32_e32 v228, v48
	v_fmamk_f32 v48, v56, 0x3fb8aa3b, v255
	v_add_f32_e32 v15, v232, v15
	v_fmamk_f32 v32, v32, 0x3fb8aa3b, v255
	v_add_f32_e32 v15, v194, v15
	v_exp_f32_e32 v231, v48
	v_fmamk_f32 v48, v59, 0x3fb8aa3b, v255
	v_add_f32_e32 v15, v195, v15
	v_exp_f32_e32 v72, v32
	v_fmamk_f32 v32, v176, 0x3fb8aa3b, v255
	v_add_f32_e32 v15, v196, v15
	v_exp_f32_e32 v234, v48
	v_fmamk_f32 v48, v58, 0x3fb8aa3b, v255
	v_add_f32_e32 v15, v197, v15
	v_exp_f32_e32 v73, v32
	v_fmamk_f32 v32, v99, 0x3fb8aa3b, v255
	v_add_f32_e32 v15, v200, v15
	v_exp_f32_e32 v236, v48
	v_fmamk_f32 v48, v61, 0x3fb8aa3b, v255
	v_add_f32_e32 v15, v213, v15
	v_exp_f32_e32 v74, v32
	v_fmamk_f32 v32, v37, 0x3fb8aa3b, v255
	v_add_f32_e32 v15, v216, v15
	v_exp_f32_e32 v237, v48
	v_fmamk_f32 v48, v60, 0x3fb8aa3b, v255
	v_add_f32_e32 v15, v220, v15
	v_exp_f32_e32 v75, v32
	v_fmamk_f32 v32, v36, 0x3fb8aa3b, v255
	v_add_f32_e32 v15, v224, v15
	v_exp_f32_e32 v238, v48
	v_fmamk_f32 v48, v63, 0x3fb8aa3b, v255
	v_add_f32_e32 v15, v227, v15
	v_exp_f32_e32 v76, v32
	v_fmamk_f32 v32, v39, 0x3fb8aa3b, v255
	v_add_f32_e32 v15, v228, v15
	v_exp_f32_e32 v69, v48
	v_fmamk_f32 v48, v62, 0x3fb8aa3b, v255
	v_add_f32_e32 v15, v231, v15
	v_exp_f32_e32 v77, v32
	v_fmamk_f32 v32, v38, 0x3fb8aa3b, v255
	v_add_f32_e32 v15, v234, v15
	v_exp_f32_e32 v70, v48
	v_fmamk_f32 v48, v98, 0x3fb8aa3b, v255
	v_add_f32_e32 v15, v236, v15
	v_exp_f32_e32 v78, v32
	v_fmamk_f32 v32, v41, 0x3fb8aa3b, v255
	v_add_f32_e32 v15, v237, v15
	v_exp_f32_e32 v71, v48
	v_fmamk_f32 v16, v16, 0x3fb8aa3b, v255
	v_add_f32_e32 v15, v238, v15
	v_exp_f32_e32 v79, v32
	v_fmamk_f32 v32, v40, 0x3fb8aa3b, v255
	v_add_f32_e32 v15, v69, v15
	v_exp_f32_e32 v55, v16
	v_fmamk_f32 v16, v19, 0x3fb8aa3b, v255
	v_add_f32_e32 v15, v70, v15
	v_exp_f32_e32 v96, v32
	v_fmamk_f32 v32, v43, 0x3fb8aa3b, v255
	v_add_f32_e32 v15, v71, v15
	v_exp_f32_e32 v56, v16
	v_fmamk_f32 v16, v18, 0x3fb8aa3b, v255
	v_add_f32_e32 v15, v72, v15
	v_exp_f32_e32 v97, v32
	v_fmamk_f32 v32, v42, 0x3fb8aa3b, v255
	v_add_f32_e32 v15, v73, v15
	v_exp_f32_e32 v58, v16
	v_fmamk_f32 v16, v21, 0x3fb8aa3b, v255
	v_add_f32_e32 v15, v74, v15
	v_exp_f32_e32 v98, v32
	v_fmamk_f32 v32, v45, 0x3fb8aa3b, v255
	v_add_f32_e32 v15, v75, v15
	v_exp_f32_e32 v59, v16
	v_fmamk_f32 v16, v20, 0x3fb8aa3b, v255
	v_add_f32_e32 v15, v76, v15
	v_exp_f32_e32 v99, v32
	v_fmamk_f32 v32, v44, 0x3fb8aa3b, v255
	v_add_f32_e32 v15, v77, v15
	v_exp_f32_e32 v62, v16
	v_fmamk_f32 v16, v23, 0x3fb8aa3b, v255
	v_add_f32_e32 v15, v78, v15
	v_exp_f32_e32 v193, v32
	v_fmamk_f32 v32, v47, 0x3fb8aa3b, v255
	v_add_f32_e32 v15, v79, v15
	v_exp_f32_e32 v57, v16
	v_fmamk_f32 v16, v22, 0x3fb8aa3b, v255
	v_add_f32_e32 v15, v96, v15
	v_exp_f32_e32 v51, v32
	v_fmamk_f32 v32, v46, 0x3fb8aa3b, v255
	v_add_f32_e32 v15, v97, v15
	v_fmamk_f32 v17, v17, 0x3fb8aa3b, v255
	v_exp_f32_e32 v60, v16
	v_fmamk_f32 v16, v25, 0x3fb8aa3b, v255
	v_add_f32_e32 v15, v98, v15
	v_exp_f32_e32 v53, v32
	v_add_f32_e32 v15, v99, v15
	v_exp_f32_e32 v54, v17
	v_exp_f32_e32 v61, v16
	v_fmamk_f32 v16, v24, 0x3fb8aa3b, v255
	v_add_f32_e32 v15, v193, v15
	v_add_f32_e32 v15, v51, v15
	v_exp_f32_e32 v63, v16
	v_fmamk_f32 v16, v27, 0x3fb8aa3b, v255
	v_add_f32_e32 v15, v53, v15
	v_add_f32_e32 v15, v54, v15
	v_exp_f32_e32 v64, v16
	v_fmamk_f32 v16, v26, 0x3fb8aa3b, v255
	v_add_f32_e32 v15, v55, v15
	v_add_f32_e32 v15, v56, v15
	v_exp_f32_e32 v65, v16
	v_fmamk_f32 v16, v29, 0x3fb8aa3b, v255
	v_add_f32_e32 v15, v58, v15
	v_fmamk_f32 v2, v2, 0x3fb8aa3b, v255
	v_add_f32_e32 v15, v59, v15
	v_exp_f32_e32 v66, v16
	v_fmamk_f32 v16, v28, 0x3fb8aa3b, v255
	v_add_f32_e32 v15, v62, v15
	v_exp_f32_e32 v41, v2
	v_fmamk_f32 v2, v5, 0x3fb8aa3b, v255
	v_add_f32_e32 v15, v57, v15
	v_exp_f32_e32 v67, v16
	v_fmamk_f32 v16, v31, 0x3fb8aa3b, v255
	v_add_f32_e32 v15, v60, v15
	v_exp_f32_e32 v42, v2
	v_fmamk_f32 v2, v4, 0x3fb8aa3b, v255
	v_add_f32_e32 v15, v61, v15
	v_exp_f32_e32 v36, v16
	v_fmamk_f32 v16, v30, 0x3fb8aa3b, v255
	v_add_f32_e32 v15, v63, v15
	v_exp_f32_e32 v44, v2
	v_fmamk_f32 v2, v7, 0x3fb8aa3b, v255
	v_add_f32_e32 v15, v64, v15
	v_exp_f32_e32 v37, v16
	v_fmamk_f32 v16, v235, 0x3fb8aa3b, v255
	v_add_f32_e32 v15, v65, v15
	v_fmamk_f32 v1, v1, 0x3fb8aa3b, v255
	v_exp_f32_e32 v43, v2
	v_fmamk_f32 v2, v6, 0x3fb8aa3b, v255
	v_add_f32_e32 v15, v66, v15
	v_exp_f32_e32 v38, v16
	v_fmamk_f32 v3, v3, 0x3fb8aa3b, v255
	v_add_f32_e32 v15, v67, v15
	v_exp_f32_e32 v39, v1
	v_exp_f32_e32 v45, v2
	v_fmamk_f32 v2, v9, 0x3fb8aa3b, v255
	v_add_f32_e32 v1, v36, v15
	v_exp_f32_e32 v40, v3
	v_add_f32_e32 v1, v37, v1
	v_exp_f32_e32 v46, v2
	v_fmamk_f32 v2, v8, 0x3fb8aa3b, v255
	v_add_f32_e32 v1, v38, v1
	v_add_f32_e32 v1, v39, v1
	v_exp_f32_e32 v47, v2
	v_fmamk_f32 v2, v11, 0x3fb8aa3b, v255
	v_add_f32_e32 v1, v40, v1
	v_add_f32_e32 v1, v41, v1
	v_exp_f32_e32 v48, v2
	v_fmamk_f32 v2, v10, 0x3fb8aa3b, v255
	v_add_f32_e32 v1, v42, v1
	v_add_f32_e32 v1, v44, v1
	v_exp_f32_e32 v49, v2
	v_fmamk_f32 v2, v13, 0x3fb8aa3b, v255
	v_add_f32_e32 v1, v43, v1
	v_add_f32_e32 v1, v45, v1
	v_exp_f32_e32 v50, v2
	v_fmamk_f32 v2, v12, 0x3fb8aa3b, v255
	v_add_f32_e32 v1, v46, v1
	v_add_f32_e32 v1, v47, v1
	v_exp_f32_e32 v52, v2
	v_add_f32_e32 v1, v48, v1
	v_add_f32_e32 v1, v49, v1
	v_add_f32_e32 v1, v50, v1
	v_fmamk_f32 v14, v14, 0x3fb8aa3b, v255
	v_add_f32_e32 v68, v52, v1
	ds_bpermute_b32 v176, v114, v68
	v_exp_f32_e32 v32, v14
	s_cbranch_vccnz .Lzero_O
	s_movk_i32 s34, 0x110
	v_mad_u64_u32 v[244:245], s[34:35], v34, s34, v[102:103]
	ds_read_b128 v[0:3], v244 offset:96
	ds_read_b128 v[4:7], v244 offset:64
	ds_read_b128 v[8:11], v244
	ds_read_b128 v[12:15], v244 offset:32
	s_waitcnt lgkmcnt(3)
	v_pk_mul_f32 v[30:31], v[32:33], v[2:3] op_sel_hi:[0,1]
	v_pk_mul_f32 v[28:29], v[32:33], v[0:1] op_sel_hi:[0,1]
	s_waitcnt lgkmcnt(2)
	v_pk_mul_f32 v[26:27], v[32:33], v[6:7] op_sel_hi:[0,1]
	v_pk_mul_f32 v[24:25], v[32:33], v[4:5] op_sel_hi:[0,1]
	ds_read_b128 v[0:3], v244 offset:192
	ds_read_b128 v[4:7], v244 offset:224
	ds_read_b128 v[240:243], v244 offset:128
	ds_read_b128 v[244:247], v244 offset:160
	s_waitcnt lgkmcnt(4)
	v_pk_mul_f32 v[22:23], v[32:33], v[14:15] op_sel_hi:[0,1]
	v_pk_mul_f32 v[20:21], v[32:33], v[12:13] op_sel_hi:[0,1]
	v_pk_mul_f32 v[18:19], v[32:33], v[10:11] op_sel_hi:[0,1]
	v_pk_mul_f32 v[16:17], v[32:33], v[8:9] op_sel_hi:[0,1]
	s_waitcnt lgkmcnt(2)
	v_pk_mul_f32 v[14:15], v[32:33], v[6:7] op_sel_hi:[0,1]
	v_pk_mul_f32 v[12:13], v[32:33], v[4:5] op_sel_hi:[0,1]
	v_pk_mul_f32 v[10:11], v[32:33], v[2:3] op_sel_hi:[0,1]
	v_pk_mul_f32 v[8:9], v[32:33], v[0:1] op_sel_hi:[0,1]
	s_waitcnt lgkmcnt(0)
	v_pk_mul_f32 v[6:7], v[32:33], v[246:247] op_sel_hi:[0,1]
	v_pk_mul_f32 v[4:5], v[32:33], v[244:245] op_sel_hi:[0,1]
	v_pk_mul_f32 v[2:3], v[32:33], v[242:243] op_sel_hi:[0,1]
	v_pk_mul_f32 v[0:1], v[32:33], v[240:241] op_sel_hi:[0,1]
	s_branch .LBB0_276
.Lzero_O:
	v_mov_b32_e32 v1, 0
	v_mov_b32_e32 v2, 0
	v_mov_b32_e32 v3, 0
	v_mov_b32_e32 v4, 0
	v_mov_b32_e32 v5, 0
	v_mov_b32_e32 v6, 0
	v_mov_b32_e32 v7, 0
	v_mov_b32_e32 v8, 0
	v_mov_b32_e32 v9, 0
	v_mov_b32_e32 v10, 0
	v_mov_b32_e32 v11, 0
	v_mov_b32_e32 v12, 0
	v_mov_b32_e32 v13, 0
	v_mov_b32_e32 v14, 0
	v_mov_b32_e32 v15, 0
	v_mov_b32_e32 v16, 0
	v_mov_b32_e32 v17, 0
	v_mov_b32_e32 v18, 0
	v_mov_b32_e32 v19, 0
	v_mov_b32_e32 v20, 0
	v_mov_b32_e32 v21, 0
	v_mov_b32_e32 v22, 0
	v_mov_b32_e32 v23, 0
	v_mov_b32_e32 v24, 0
	v_mov_b32_e32 v25, 0
	v_mov_b32_e32 v26, 0
	v_mov_b32_e32 v27, 0
	v_mov_b32_e32 v28, 0
	v_mov_b32_e32 v29, 0
	v_mov_b32_e32 v30, 0
	v_mov_b32_e32 v31, 0
